# P4 queue order variant B: S5 output items before the qb<=2 attention units
# baseline (speedup 1.0000x reference)
; __global__ void __launch_bounds__(512, 2) fwd_kernel(Args A0) {
;     ...
;           static constexpr unsigned char ORD[108] = {60, 61, 62, 63, 56, 57, 58, 59, 52, 53, 54, 55, 48, 49, 50, 51, 44, 45, 46, 47, 40, 41, 42, 43, 36, 37, 38, 39, 32, 33, 34, 35, 28, 29, 30, 31, 64, 65, 66, 67, 68, 69, 70, 71, 72, 73, 74, 75, 24, 76, 77, 25, 78, 79, 26, 80, 81, 27, 82, 83, 20, 84, 85, 21, 86, 87, 22, 88, 89, 23, 90, 91, 16, 92, 93, 17, 94, 95, 18, 96, 97, 19, 98, 99, 12, 100, 101, 13, 102, 103, 14, 104, 105, 15, 106, 107, 8, 9, 10, 11, 4, 5, 6, 7, 0, 1, 2, 3};
_ZZ10fwd_kernel4ArgsE3ORD.const:
	.ascii	"\074\075\076\077\070\071\072\073\064\065\066\067\060\061\062\063\054\055\056\057\050\051\052\053\044\045\046\047\040\041\042\043\034\035\036\037\030\031\032\033\024\025\026\027\100\101\102\103\104\105\106\107\020\021\022\023\014\015\016\017\114\115\116\117\120\121\122\123\124\125\126\127\130\131\132\133\134\135\136\137\140\141\142\143\144\145\146\147\150\151\152\153\010\011\012\013\004\005\006\007\000\001\002\003\110\111\112\113"
	.size	_ZZ10fwd_kernel4ArgsE3ORD.const, 108

; __global__ void __launch_bounds__(512, 2) fwd_kernel(Args A0) {
;     ...
;           static constexpr unsigned char ORD[108] = {60, 61, 62, 63, 56, 57, 58, 59, 52, 53, 54, 55, 48, 49, 50, 51, 44, 45, 46, 47, 40, 41, 42, 43, 36, 37, 38, 39, 32, 33, 34, 35, 28, 29, 30, 31, 64, 65, 66, 67, 68, 69, 70, 71, 72, 73, 74, 75, 24, 76, 77, 25, 78, 79, 26, 80, 81, 27, 82, 83, 20, 84, 85, 21, 86, 87, 22, 88, 89, 23, 90, 91, 16, 92, 93, 17, 94, 95, 18, 96, 97, 19, 98, 99, 12, 100, 101, 13, 102, 103, 14, 104, 105, 15, 106, 107, 8, 9, 10, 11, 4, 5, 6, 7, 0, 1, 2, 3};
	.type	__hip_cuid_af2ee39715b257f4,@object
